# nt cache policy on the read-once f32 input loads of the chunk conversion and on the write-once f32 output stores
# baseline (speedup 1.0000x reference)
;     __device__ __forceinline__ void fused(f32x4 (&acc)[2][2][4][2], const Unit& u, int wr, int wc, int fr, int fq, LAS unsigned char* lds, int wid, int lane) const {
;     ...
;         asm volatile("s_waitcnt lgkmcnt(0)" ::: "memory"); __builtin_amdgcn_s_barrier(); asm volatile("" ::: "memory");
;         f32x4 gv[2][2], bv[2][2];
; #pragma unroll
;         for (int bj = 0; bj < 2; ++bj)
; #pragma unroll
;             for (int n = 0; n < 2; ++n) { gv[bj][n] = *(const f32x4*)(gam + col0 + bj * HALF + 4 * n); bv[bj][n] = *(const f32x4*)(bet + col0 + bj * HALF + 4 * n); }
; #pragma unroll
;         for (int ai = 0; ai < 2; ++ai)
; #pragma unroll
;             for (int m = 0; m < 4; ++m) { const int r = ai * HALF + wr * 64 + m * 16 + fr; const f32x2 sr = S[r]; const size_t off = (size_t)(u.pm * BM + r) * D + col0;
; #pragma unroll
;                 for (int bj = 0; bj < 2; ++bj) {
;                     const f32x4 y0 = (acc[ai][bj][m][0] - sr.x) * sr.y * gv[bj][0] + bv[bj][0], y1 = (acc[ai][bj][m][1] - sr.x) * sr.y * gv[bj][1] + bv[bj][1];
;                     if (xout) { *(f32x4*)(xout + off + bj * HALF) = y0; *(f32x4*)(xout + off + bj * HALF + 4) = y1; }
;                     else { u32x4 hw; hw.x = cvt_pk_h(y0[0], y0[1]); hw.y = cvt_pk_h(y0[2], y0[3]); hw.z = cvt_pk_h(y1[0], y1[1]); hw.w = cvt_pk_h(y1[2], y1[3]); *(u32x4*)(X16 + off + bj * HALF) = hw; } }
.LBB0_210:
	s_or_b64 exec, exec, s[42:43]
	s_ashr_i32 s31, s30, 31
	s_lshl_b64 s[4:5], s[30:31], 26
	v_readlane_b32 s6, v254, 54
	v_readlane_b32 s7, v254, 55
	s_add_u32 s6, s6, s4
	s_addc_u32 s7, s7, s5
	s_and_b64 s[4:5], s[24:25], exec
	s_cselect_b32 s43, s7, 0
	s_cselect_b32 s42, s6, 0
	s_lshl_b32 s4, s12, 10
	s_ashr_i32 s5, s4, 31
	s_lshl_b64 s[4:5], s[4:5], 2
	v_readlane_b32 s6, v255, 54
	v_readlane_b32 s7, v255, 55
	s_add_u32 s8, s6, s4
	s_addc_u32 s9, s7, s5
	v_readlane_b32 s6, v255, 56
	v_readlane_b32 s7, v255, 57
	s_add_u32 s4, s6, s4
	s_addc_u32 s5, s7, s5
	v_lshlrev_b64 v[48:49], 2, v[172:173]
	s_waitcnt lgkmcnt(0)
	s_barrier
	v_lshl_add_u64 v[52:53], s[8:9], 0, v[48:49]
	v_lshl_add_u64 v[140:141], s[4:5], 0, v[48:49]
	global_load_dwordx4 v[144:147], v[52:53], off offset:16
	global_load_dwordx4 v[152:155], v[52:53], off
	global_load_dwordx4 v[156:159], v[140:141], off
	global_load_dwordx4 v[148:151], v[140:141], off offset:16
	global_load_dwordx4 v[48:51], v[52:53], off offset:528
	global_load_dwordx4 v[136:139], v[52:53], off offset:512
	s_nop 0
	global_load_dwordx4 v[52:55], v[140:141], off offset:528
	s_nop 0
	global_load_dwordx4 v[140:143], v[140:141], off offset:512
	v_lshl_add_u32 v160, v171, 3, 0
	ds_read_b64 v[192:193], v160 offset:8192
	v_add_u32_e32 v190, s23, v171
	v_ashrrev_i32_e32 v191, 31, v190
	v_lshlrev_b64 v[194:195], 10, v[190:191]
	v_lshl_add_u64 v[194:195], v[194:195], 0, v[172:173]
	s_waitcnt lgkmcnt(0)
	v_sub_f32_e32 v31, v31, v192
	v_sub_f32_e32 v30, v30, v192
	v_sub_f32_e32 v29, v29, v192
	v_sub_f32_e32 v28, v28, v192
	v_sub_f32_e32 v27, v27, v192
	v_sub_f32_e32 v26, v26, v192
	v_sub_f32_e32 v25, v25, v192
	v_sub_f32_e32 v24, v24, v192
	v_pk_mul_f32 v[28:29], v[192:193], v[28:29] op_sel:[1,0]
	v_pk_mul_f32 v[30:31], v[192:193], v[30:31] op_sel:[1,0]
	v_pk_mul_f32 v[24:25], v[192:193], v[24:25] op_sel:[1,0]
	v_pk_mul_f32 v[26:27], v[192:193], v[26:27] op_sel:[1,0]
	s_cmp_lg_u64 s[42:43], 0
	s_cselect_b64 s[44:45], -1, 0
	s_cmp_eq_u64 s[42:43], 0
	v_lshl_add_u64 v[194:195], v[194:195], 2, s[42:43]
	s_waitcnt vmcnt(5)
	v_pk_fma_f32 v[30:31], v[154:155], v[30:31], v[158:159]
	v_pk_fma_f32 v[28:29], v[152:153], v[28:29], v[156:157]
	s_waitcnt vmcnt(4)
	v_pk_fma_f32 v[26:27], v[146:147], v[26:27], v[150:151]
	v_pk_fma_f32 v[24:25], v[144:145], v[24:25], v[148:149]
	s_cbranch_scc1 .LBB0_522
	global_store_dwordx4 v[194:195], v[28:31], off nt
	global_store_dwordx4 v[194:195], v[24:27], off offset:16 nt
	s_cbranch_execnz .LBB0_213

;     __device__ __forceinline__ void fused(f32x4 (&acc)[2][2][4][2], const Unit& u, int wr, int wc, int fr, int fq, LAS unsigned char* lds, int wid, int lane) const {
;     ...
;                 for (int bj = 0; bj < 2; ++bj) {
;                     const f32x4 y0 = (acc[ai][bj][m][0] - sr.x) * sr.y * gv[bj][0] + bv[bj][0], y1 = (acc[ai][bj][m][1] - sr.x) * sr.y * gv[bj][1] + bv[bj][1];
;                     if (xout) { *(f32x4*)(xout + off + bj * HALF) = y0; *(f32x4*)(xout + off + bj * HALF + 4) = y1; }
;                     else { u32x4 hw; hw.x = cvt_pk_h(y0[0], y0[1]); hw.y = cvt_pk_h(y0[2], y0[3]); hw.z = cvt_pk_h(y1[0], y1[1]); hw.w = cvt_pk_h(y1[2], y1[3]); *(u32x4*)(X16 + off + bj * HALF) = hw; } }
.LBB0_213:
	s_nop 0
	v_mov_b32_e32 v24, v193
	v_mov_b32_e32 v25, v193
	v_sub_f32_e32 v15, v15, v192
	v_sub_f32_e32 v14, v14, v192
	v_sub_f32_e32 v13, v13, v192
	v_sub_f32_e32 v12, v12, v192
	v_mov_b32_e32 v26, v193
	v_mov_b32_e32 v27, v193
	v_sub_f32_e32 v11, v11, v192
	v_sub_f32_e32 v10, v10, v192
	v_sub_f32_e32 v9, v9, v192
	v_sub_f32_e32 v8, v8, v192
	v_pk_mul_f32 v[12:13], v[24:25], v[12:13]
	v_pk_mul_f32 v[14:15], v[26:27], v[14:15]
	v_pk_mul_f32 v[8:9], v[24:25], v[8:9]
	v_pk_mul_f32 v[10:11], v[26:27], v[10:11]
	v_cndmask_b32_e64 v24, 0, 1, s[44:45]
	s_waitcnt vmcnt(0)
	v_pk_fma_f32 v[14:15], v[138:139], v[14:15], v[142:143]
	v_pk_fma_f32 v[12:13], v[136:137], v[12:13], v[140:141]
	v_pk_fma_f32 v[10:11], v[50:51], v[10:11], v[54:55]
	v_cmp_ne_u32_e64 s[40:41], 1, v24
	s_andn2_b64 vcc, exec, s[44:45]
	v_pk_fma_f32 v[8:9], v[48:49], v[8:9], v[52:53]
	s_cbranch_vccnz .LBB0_523
	global_store_dwordx4 v[194:195], v[12:15], off offset:512 nt
	global_store_dwordx4 v[194:195], v[8:11], off offset:528 nt
	s_cbranch_execnz .LBB0_216

;     __device__ __forceinline__ void fused(f32x4 (&acc)[2][2][4][2], const Unit& u, int wr, int wc, int fr, int fq, LAS unsigned char* lds, int wid, int lane) const {
;     ...
;             for (int m = 0; m < 4; ++m) { const int r = ai * HALF + wr * 64 + m * 16 + fr; const f32x2 sr = S[r]; const size_t off = (size_t)(u.pm * BM + r) * D + col0;
; #pragma unroll
;                 for (int bj = 0; bj < 2; ++bj) {
;                     const f32x4 y0 = (acc[ai][bj][m][0] - sr.x) * sr.y * gv[bj][0] + bv[bj][0], y1 = (acc[ai][bj][m][1] - sr.x) * sr.y * gv[bj][1] + bv[bj][1];
;                     if (xout) { *(f32x4*)(xout + off + bj * HALF) = y0; *(f32x4*)(xout + off + bj * HALF + 4) = y1; }
;                     else { u32x4 hw; hw.x = cvt_pk_h(y0[0], y0[1]); hw.y = cvt_pk_h(y0[2], y0[3]); hw.z = cvt_pk_h(y1[0], y1[1]); hw.w = cvt_pk_h(y1[2], y1[3]); *(u32x4*)(X16 + off + bj * HALF) = hw; } }
.LBB0_216:
	ds_read_b64 v[24:25], v160 offset:8320
	v_add3_u32 v8, s23, v171, 16
	v_ashrrev_i32_e32 v9, 31, v8
	v_lshlrev_b64 v[8:9], 10, v[8:9]
	v_lshl_add_u64 v[26:27], v[8:9], 0, v[172:173]
	s_waitcnt lgkmcnt(0)
	v_sub_f32_e32 v9, v23, v24
	v_sub_f32_e32 v8, v22, v24
	v_sub_f32_e32 v11, v21, v24
	v_sub_f32_e32 v10, v20, v24
	v_pk_mul_f32 v[12:13], v[24:25], v[10:11] op_sel:[1,0]
	v_pk_mul_f32 v[8:9], v[24:25], v[8:9] op_sel:[1,0]
	v_sub_f32_e32 v15, v17, v24
	v_pk_fma_f32 v[10:11], v[154:155], v[8:9], v[158:159]
	v_pk_fma_f32 v[8:9], v[152:153], v[12:13], v[156:157]
	v_sub_f32_e32 v13, v19, v24
	v_sub_f32_e32 v12, v18, v24
	v_sub_f32_e32 v14, v16, v24
	v_pk_mul_f32 v[16:17], v[24:25], v[14:15] op_sel:[1,0]
	v_pk_mul_f32 v[12:13], v[24:25], v[12:13] op_sel:[1,0]
	s_and_b64 vcc, exec, s[40:41]
	v_pk_fma_f32 v[14:15], v[146:147], v[12:13], v[150:151]
	v_pk_fma_f32 v[12:13], v[144:145], v[16:17], v[148:149]
	v_lshl_add_u64 v[16:17], v[26:27], 2, s[42:43]
	s_cbranch_vccnz .LBB0_524
	global_store_dwordx4 v[16:17], v[8:11], off nt
	global_store_dwordx4 v[16:17], v[12:15], off offset:16 nt
	s_cbranch_execnz .LBB0_219

;     __device__ __forceinline__ void fused(f32x4 (&acc)[2][2][4][2], const Unit& u, int wr, int wc, int fr, int fq, LAS unsigned char* lds, int wid, int lane) const {
;     ...
;             for (int m = 0; m < 4; ++m) { const int r = ai * HALF + wr * 64 + m * 16 + fr; const f32x2 sr = S[r]; const size_t off = (size_t)(u.pm * BM + r) * D + col0;
; #pragma unroll
;                 for (int bj = 0; bj < 2; ++bj) {
;                     const f32x4 y0 = (acc[ai][bj][m][0] - sr.x) * sr.y * gv[bj][0] + bv[bj][0], y1 = (acc[ai][bj][m][1] - sr.x) * sr.y * gv[bj][1] + bv[bj][1];
;                     if (xout) { *(f32x4*)(xout + off + bj * HALF) = y0; *(f32x4*)(xout + off + bj * HALF + 4) = y1; }
;                     else { u32x4 hw; hw.x = cvt_pk_h(y0[0], y0[1]); hw.y = cvt_pk_h(y0[2], y0[3]); hw.z = cvt_pk_h(y1[0], y1[1]); hw.w = cvt_pk_h(y1[2], y1[3]); *(u32x4*)(X16 + off + bj * HALF) = hw; } }
.LBB0_219:
	s_nop 1
	v_mov_b32_e32 v8, v25
	v_mov_b32_e32 v9, v25
	v_sub_f32_e32 v7, v7, v24
	v_sub_f32_e32 v6, v6, v24
	v_sub_f32_e32 v5, v5, v24
	v_sub_f32_e32 v4, v4, v24
	v_mov_b32_e32 v10, v25
	v_mov_b32_e32 v11, v25
	v_sub_f32_e32 v3, v3, v24
	v_sub_f32_e32 v2, v2, v24
	v_sub_f32_e32 v1, v1, v24
	v_sub_f32_e32 v0, v0, v24
	v_pk_mul_f32 v[4:5], v[8:9], v[4:5]
	v_pk_mul_f32 v[6:7], v[10:11], v[6:7]
	v_pk_mul_f32 v[0:1], v[8:9], v[0:1]
	v_pk_mul_f32 v[2:3], v[10:11], v[2:3]
	v_pk_fma_f32 v[6:7], v[138:139], v[6:7], v[142:143]
	v_pk_fma_f32 v[4:5], v[136:137], v[4:5], v[140:141]
	v_pk_fma_f32 v[2:3], v[50:51], v[2:3], v[54:55]
	s_and_b64 vcc, exec, s[40:41]
	v_pk_fma_f32 v[0:1], v[48:49], v[0:1], v[52:53]
	s_cbranch_vccnz .LBB0_525
	global_store_dwordx4 v[16:17], v[4:7], off offset:512 nt
	global_store_dwordx4 v[16:17], v[0:3], off offset:528 nt
	s_cbranch_execnz .LBB0_222

;     __device__ __forceinline__ void fused(f32x4 (&acc)[2][2][4][2], const Unit& u, int wr, int wc, int fr, int fq, LAS unsigned char* lds, int wid, int lane) const {
;     ...
;             for (int m = 0; m < 4; ++m) { const int r = ai * HALF + wr * 64 + m * 16 + fr; const f32x2 sr = S[r]; const size_t off = (size_t)(u.pm * BM + r) * D + col0;
; #pragma unroll
;                 for (int bj = 0; bj < 2; ++bj) {
;                     const f32x4 y0 = (acc[ai][bj][m][0] - sr.x) * sr.y * gv[bj][0] + bv[bj][0], y1 = (acc[ai][bj][m][1] - sr.x) * sr.y * gv[bj][1] + bv[bj][1];
;                     if (xout) { *(f32x4*)(xout + off + bj * HALF) = y0; *(f32x4*)(xout + off + bj * HALF + 4) = y1; }
;                     else { u32x4 hw; hw.x = cvt_pk_h(y0[0], y0[1]); hw.y = cvt_pk_h(y0[2], y0[3]); hw.z = cvt_pk_h(y1[0], y1[1]); hw.w = cvt_pk_h(y1[2], y1[3]); *(u32x4*)(X16 + off + bj * HALF) = hw; } }
.LBB0_222:
	ds_read_b64 v[8:9], v160 offset:8448
	v_add3_u32 v0, s23, v171, 32
	v_ashrrev_i32_e32 v1, 31, v0
	v_lshlrev_b64 v[0:1], 10, v[0:1]
	v_lshl_add_u64 v[10:11], v[0:1], 0, v[172:173]
	s_waitcnt lgkmcnt(0)
	v_sub_f32_e32 v1, v79, v8
	v_sub_f32_e32 v0, v78, v8
	v_sub_f32_e32 v3, v77, v8
	v_sub_f32_e32 v2, v76, v8
	v_pk_mul_f32 v[4:5], v[8:9], v[2:3] op_sel:[1,0]
	v_pk_mul_f32 v[0:1], v[8:9], v[0:1] op_sel:[1,0]
	v_sub_f32_e32 v7, v73, v8
	v_pk_fma_f32 v[2:3], v[154:155], v[0:1], v[158:159]
	v_pk_fma_f32 v[0:1], v[152:153], v[4:5], v[156:157]
	v_sub_f32_e32 v5, v75, v8
	v_sub_f32_e32 v4, v74, v8
	v_sub_f32_e32 v6, v72, v8
	v_pk_mul_f32 v[12:13], v[8:9], v[6:7] op_sel:[1,0]
	v_pk_mul_f32 v[4:5], v[8:9], v[4:5] op_sel:[1,0]
	s_and_b64 vcc, exec, s[40:41]
	v_pk_fma_f32 v[6:7], v[146:147], v[4:5], v[150:151]
	v_pk_fma_f32 v[4:5], v[144:145], v[12:13], v[148:149]
	v_lshl_add_u64 v[10:11], v[10:11], 2, s[42:43]
	s_cbranch_vccnz .LBB0_526
	global_store_dwordx4 v[10:11], v[0:3], off nt
	global_store_dwordx4 v[10:11], v[4:7], off offset:16 nt
	s_cbranch_execnz .LBB0_225

;     __device__ __forceinline__ void fused(f32x4 (&acc)[2][2][4][2], const Unit& u, int wr, int wc, int fr, int fq, LAS unsigned char* lds, int wid, int lane) const {
;     ...
;             for (int m = 0; m < 4; ++m) { const int r = ai * HALF + wr * 64 + m * 16 + fr; const f32x2 sr = S[r]; const size_t off = (size_t)(u.pm * BM + r) * D + col0;
; #pragma unroll
;                 for (int bj = 0; bj < 2; ++bj) {
;                     const f32x4 y0 = (acc[ai][bj][m][0] - sr.x) * sr.y * gv[bj][0] + bv[bj][0], y1 = (acc[ai][bj][m][1] - sr.x) * sr.y * gv[bj][1] + bv[bj][1];
;                     if (xout) { *(f32x4*)(xout + off + bj * HALF) = y0; *(f32x4*)(xout + off + bj * HALF + 4) = y1; }
;                     else { u32x4 hw; hw.x = cvt_pk_h(y0[0], y0[1]); hw.y = cvt_pk_h(y0[2], y0[3]); hw.z = cvt_pk_h(y1[0], y1[1]); hw.w = cvt_pk_h(y1[2], y1[3]); *(u32x4*)(X16 + off + bj * HALF) = hw; } }
.LBB0_225:
	s_nop 0
	v_mov_b32_e32 v4, v9
	v_mov_b32_e32 v5, v9
	v_sub_f32_e32 v1, v71, v8
	v_sub_f32_e32 v0, v70, v8
	v_sub_f32_e32 v3, v69, v8
	v_sub_f32_e32 v2, v68, v8
	v_mov_b32_e32 v12, v9
	v_mov_b32_e32 v13, v9
	v_pk_mul_f32 v[6:7], v[4:5], v[2:3]
	v_pk_mul_f32 v[0:1], v[12:13], v[0:1]
	v_sub_f32_e32 v9, v65, v8
	v_pk_fma_f32 v[2:3], v[138:139], v[0:1], v[142:143]
	v_pk_fma_f32 v[0:1], v[136:137], v[6:7], v[140:141]
	v_sub_f32_e32 v7, v67, v8
	v_sub_f32_e32 v6, v66, v8
	v_sub_f32_e32 v8, v64, v8
	v_pk_mul_f32 v[4:5], v[4:5], v[8:9]
	v_pk_mul_f32 v[6:7], v[12:13], v[6:7]
	s_and_b64 vcc, exec, s[40:41]
	v_pk_fma_f32 v[6:7], v[50:51], v[6:7], v[54:55]
	v_pk_fma_f32 v[4:5], v[48:49], v[4:5], v[52:53]
	s_cbranch_vccnz .LBB0_527
	global_store_dwordx4 v[10:11], v[0:3], off offset:512 nt
	global_store_dwordx4 v[10:11], v[4:7], off offset:528 nt
	s_cbranch_execnz .LBB0_228

;     __device__ __forceinline__ void fused(f32x4 (&acc)[2][2][4][2], const Unit& u, int wr, int wc, int fr, int fq, LAS unsigned char* lds, int wid, int lane) const {
;     ...
;             for (int m = 0; m < 4; ++m) { const int r = ai * HALF + wr * 64 + m * 16 + fr; const f32x2 sr = S[r]; const size_t off = (size_t)(u.pm * BM + r) * D + col0;
; #pragma unroll
;                 for (int bj = 0; bj < 2; ++bj) {
;                     const f32x4 y0 = (acc[ai][bj][m][0] - sr.x) * sr.y * gv[bj][0] + bv[bj][0], y1 = (acc[ai][bj][m][1] - sr.x) * sr.y * gv[bj][1] + bv[bj][1];
;                     if (xout) { *(f32x4*)(xout + off + bj * HALF) = y0; *(f32x4*)(xout + off + bj * HALF + 4) = y1; }
;                     else { u32x4 hw; hw.x = cvt_pk_h(y0[0], y0[1]); hw.y = cvt_pk_h(y0[2], y0[3]); hw.z = cvt_pk_h(y1[0], y1[1]); hw.w = cvt_pk_h(y1[2], y1[3]); *(u32x4*)(X16 + off + bj * HALF) = hw; } }
.LBB0_228:
	ds_read_b64 v[8:9], v160 offset:8576
	s_nop 0
	v_add3_u32 v0, s23, v171, 48
	v_ashrrev_i32_e32 v1, 31, v0
	v_lshlrev_b64 v[0:1], 10, v[0:1]
	v_lshl_add_u64 v[10:11], v[0:1], 0, v[172:173]
	s_waitcnt lgkmcnt(0)
	v_sub_f32_e32 v1, v95, v8
	v_sub_f32_e32 v0, v94, v8
	v_sub_f32_e32 v3, v93, v8
	v_sub_f32_e32 v2, v92, v8
	v_pk_mul_f32 v[4:5], v[8:9], v[2:3] op_sel:[1,0]
	v_pk_mul_f32 v[0:1], v[8:9], v[0:1] op_sel:[1,0]
	v_sub_f32_e32 v7, v89, v8
	v_pk_fma_f32 v[2:3], v[154:155], v[0:1], v[158:159]
	v_pk_fma_f32 v[0:1], v[152:153], v[4:5], v[156:157]
	v_sub_f32_e32 v5, v91, v8
	v_sub_f32_e32 v4, v90, v8
	v_sub_f32_e32 v6, v88, v8
	v_pk_mul_f32 v[12:13], v[8:9], v[6:7] op_sel:[1,0]
	v_pk_mul_f32 v[4:5], v[8:9], v[4:5] op_sel:[1,0]
	s_and_b64 vcc, exec, s[40:41]
	v_pk_fma_f32 v[6:7], v[146:147], v[4:5], v[150:151]
	v_pk_fma_f32 v[4:5], v[144:145], v[12:13], v[148:149]
	v_lshl_add_u64 v[10:11], v[10:11], 2, s[42:43]
	s_cbranch_vccnz .LBB0_528
	global_store_dwordx4 v[10:11], v[0:3], off nt
	global_store_dwordx4 v[10:11], v[4:7], off offset:16 nt
	s_cbranch_execnz .LBB0_231

;     __device__ __forceinline__ void fused(f32x4 (&acc)[2][2][4][2], const Unit& u, int wr, int wc, int fr, int fq, LAS unsigned char* lds, int wid, int lane) const {
;     ...
;             for (int m = 0; m < 4; ++m) { const int r = ai * HALF + wr * 64 + m * 16 + fr; const f32x2 sr = S[r]; const size_t off = (size_t)(u.pm * BM + r) * D + col0;
; #pragma unroll
;                 for (int bj = 0; bj < 2; ++bj) {
;                     const f32x4 y0 = (acc[ai][bj][m][0] - sr.x) * sr.y * gv[bj][0] + bv[bj][0], y1 = (acc[ai][bj][m][1] - sr.x) * sr.y * gv[bj][1] + bv[bj][1];
;                     if (xout) { *(f32x4*)(xout + off + bj * HALF) = y0; *(f32x4*)(xout + off + bj * HALF + 4) = y1; }
;                     else { u32x4 hw; hw.x = cvt_pk_h(y0[0], y0[1]); hw.y = cvt_pk_h(y0[2], y0[3]); hw.z = cvt_pk_h(y1[0], y1[1]); hw.w = cvt_pk_h(y1[2], y1[3]); *(u32x4*)(X16 + off + bj * HALF) = hw; } }
.LBB0_231:
	s_nop 0
	v_mov_b32_e32 v4, v9
	v_mov_b32_e32 v5, v9
	v_sub_f32_e32 v1, v87, v8
	v_sub_f32_e32 v0, v86, v8
	v_sub_f32_e32 v3, v85, v8
	v_sub_f32_e32 v2, v84, v8
	v_mov_b32_e32 v12, v9
	v_mov_b32_e32 v13, v9
	v_pk_mul_f32 v[6:7], v[4:5], v[2:3]
	v_pk_mul_f32 v[0:1], v[12:13], v[0:1]
	v_sub_f32_e32 v9, v81, v8
	v_pk_fma_f32 v[2:3], v[138:139], v[0:1], v[142:143]
	v_pk_fma_f32 v[0:1], v[136:137], v[6:7], v[140:141]
	v_sub_f32_e32 v7, v83, v8
	v_sub_f32_e32 v6, v82, v8
	v_sub_f32_e32 v8, v80, v8
	v_pk_mul_f32 v[4:5], v[4:5], v[8:9]
	v_pk_mul_f32 v[6:7], v[12:13], v[6:7]
	s_and_b64 vcc, exec, s[40:41]
	v_pk_fma_f32 v[6:7], v[50:51], v[6:7], v[54:55]
	v_pk_fma_f32 v[4:5], v[48:49], v[4:5], v[52:53]
	s_cbranch_vccnz .LBB0_529
	global_store_dwordx4 v[10:11], v[0:3], off offset:512 nt
	global_store_dwordx4 v[10:11], v[4:7], off offset:528 nt
	s_cbranch_execnz .LBB0_234

;     __device__ __forceinline__ void fused(f32x4 (&acc)[2][2][4][2], const Unit& u, int wr, int wc, int fr, int fq, LAS unsigned char* lds, int wid, int lane) const {
;     ...
;             for (int m = 0; m < 4; ++m) { const int r = ai * HALF + wr * 64 + m * 16 + fr; const f32x2 sr = S[r]; const size_t off = (size_t)(u.pm * BM + r) * D + col0;
; #pragma unroll
;                 for (int bj = 0; bj < 2; ++bj) {
;                     const f32x4 y0 = (acc[ai][bj][m][0] - sr.x) * sr.y * gv[bj][0] + bv[bj][0], y1 = (acc[ai][bj][m][1] - sr.x) * sr.y * gv[bj][1] + bv[bj][1];
;                     if (xout) { *(f32x4*)(xout + off + bj * HALF) = y0; *(f32x4*)(xout + off + bj * HALF + 4) = y1; }
;                     else { u32x4 hw; hw.x = cvt_pk_h(y0[0], y0[1]); hw.y = cvt_pk_h(y0[2], y0[3]); hw.z = cvt_pk_h(y1[0], y1[1]); hw.w = cvt_pk_h(y1[2], y1[3]); *(u32x4*)(X16 + off + bj * HALF) = hw; } }
.LBB0_234:
	ds_read_b64 v[8:9], v160 offset:9216
	s_nop 0
	v_add_u32_e32 v0, 0x80, v190
	v_ashrrev_i32_e32 v1, 31, v0
	v_lshlrev_b64 v[0:1], 10, v[0:1]
	v_lshl_add_u64 v[10:11], v[0:1], 0, v[172:173]
	s_waitcnt lgkmcnt(0)
	v_sub_f32_e32 v1, v127, v8
	v_sub_f32_e32 v0, v126, v8
	v_sub_f32_e32 v3, v125, v8
	v_sub_f32_e32 v2, v124, v8
	v_pk_mul_f32 v[4:5], v[8:9], v[2:3] op_sel:[1,0]
	v_pk_mul_f32 v[0:1], v[8:9], v[0:1] op_sel:[1,0]
	v_sub_f32_e32 v7, v121, v8
	v_pk_fma_f32 v[2:3], v[154:155], v[0:1], v[158:159]
	v_pk_fma_f32 v[0:1], v[152:153], v[4:5], v[156:157]
	v_sub_f32_e32 v5, v123, v8
	v_sub_f32_e32 v4, v122, v8
	v_sub_f32_e32 v6, v120, v8
	v_pk_mul_f32 v[12:13], v[8:9], v[6:7] op_sel:[1,0]
	v_pk_mul_f32 v[4:5], v[8:9], v[4:5] op_sel:[1,0]
	s_and_b64 vcc, exec, s[40:41]
	v_pk_fma_f32 v[6:7], v[146:147], v[4:5], v[150:151]
	v_pk_fma_f32 v[4:5], v[144:145], v[12:13], v[148:149]
	v_lshl_add_u64 v[10:11], v[10:11], 2, s[42:43]
	s_cbranch_vccnz .LBB0_530
	global_store_dwordx4 v[10:11], v[0:3], off nt
	global_store_dwordx4 v[10:11], v[4:7], off offset:16 nt
	s_cbranch_execnz .LBB0_237

;     __device__ __forceinline__ void fused(f32x4 (&acc)[2][2][4][2], const Unit& u, int wr, int wc, int fr, int fq, LAS unsigned char* lds, int wid, int lane) const {
;     ...
;             for (int m = 0; m < 4; ++m) { const int r = ai * HALF + wr * 64 + m * 16 + fr; const f32x2 sr = S[r]; const size_t off = (size_t)(u.pm * BM + r) * D + col0;
; #pragma unroll
;                 for (int bj = 0; bj < 2; ++bj) {
;                     const f32x4 y0 = (acc[ai][bj][m][0] - sr.x) * sr.y * gv[bj][0] + bv[bj][0], y1 = (acc[ai][bj][m][1] - sr.x) * sr.y * gv[bj][1] + bv[bj][1];
;                     if (xout) { *(f32x4*)(xout + off + bj * HALF) = y0; *(f32x4*)(xout + off + bj * HALF + 4) = y1; }
;                     else { u32x4 hw; hw.x = cvt_pk_h(y0[0], y0[1]); hw.y = cvt_pk_h(y0[2], y0[3]); hw.z = cvt_pk_h(y1[0], y1[1]); hw.w = cvt_pk_h(y1[2], y1[3]); *(u32x4*)(X16 + off + bj * HALF) = hw; } }
.LBB0_237:
	s_nop 0
	v_mov_b32_e32 v4, v9
	v_mov_b32_e32 v5, v9
	v_sub_f32_e32 v1, v111, v8
	v_sub_f32_e32 v0, v110, v8
	v_sub_f32_e32 v3, v109, v8
	v_sub_f32_e32 v2, v108, v8
	v_mov_b32_e32 v12, v9
	v_mov_b32_e32 v13, v9
	v_pk_mul_f32 v[6:7], v[4:5], v[2:3]
	v_pk_mul_f32 v[0:1], v[12:13], v[0:1]
	v_sub_f32_e32 v9, v105, v8
	v_pk_fma_f32 v[2:3], v[138:139], v[0:1], v[142:143]
	v_pk_fma_f32 v[0:1], v[136:137], v[6:7], v[140:141]
	v_sub_f32_e32 v7, v107, v8
	v_sub_f32_e32 v6, v106, v8
	v_sub_f32_e32 v8, v104, v8
	v_pk_mul_f32 v[4:5], v[4:5], v[8:9]
	v_pk_mul_f32 v[6:7], v[12:13], v[6:7]
	s_and_b64 vcc, exec, s[40:41]
	v_pk_fma_f32 v[6:7], v[50:51], v[6:7], v[54:55]
	v_pk_fma_f32 v[4:5], v[48:49], v[4:5], v[52:53]
	s_cbranch_vccnz .LBB0_531
	global_store_dwordx4 v[10:11], v[0:3], off offset:512 nt
	global_store_dwordx4 v[10:11], v[4:7], off offset:528 nt
	s_cbranch_execnz .LBB0_240

;     __device__ __forceinline__ void fused(f32x4 (&acc)[2][2][4][2], const Unit& u, int wr, int wc, int fr, int fq, LAS unsigned char* lds, int wid, int lane) const {
;     ...
;             for (int m = 0; m < 4; ++m) { const int r = ai * HALF + wr * 64 + m * 16 + fr; const f32x2 sr = S[r]; const size_t off = (size_t)(u.pm * BM + r) * D + col0;
; #pragma unroll
;                 for (int bj = 0; bj < 2; ++bj) {
;                     const f32x4 y0 = (acc[ai][bj][m][0] - sr.x) * sr.y * gv[bj][0] + bv[bj][0], y1 = (acc[ai][bj][m][1] - sr.x) * sr.y * gv[bj][1] + bv[bj][1];
;                     if (xout) { *(f32x4*)(xout + off + bj * HALF) = y0; *(f32x4*)(xout + off + bj * HALF + 4) = y1; }
;                     else { u32x4 hw; hw.x = cvt_pk_h(y0[0], y0[1]); hw.y = cvt_pk_h(y0[2], y0[3]); hw.z = cvt_pk_h(y1[0], y1[1]); hw.w = cvt_pk_h(y1[2], y1[3]); *(u32x4*)(X16 + off + bj * HALF) = hw; } }
.LBB0_240:
	ds_read_b64 v[8:9], v160 offset:9344
	s_nop 0
	v_add_u32_e32 v0, 0x90, v190
	v_ashrrev_i32_e32 v1, 31, v0
	v_lshlrev_b64 v[0:1], 10, v[0:1]
	v_lshl_add_u64 v[10:11], v[0:1], 0, v[172:173]
	s_waitcnt lgkmcnt(0)
	v_sub_f32_e32 v1, v119, v8
	v_sub_f32_e32 v0, v118, v8
	v_sub_f32_e32 v3, v117, v8
	v_sub_f32_e32 v2, v116, v8
	v_pk_mul_f32 v[4:5], v[8:9], v[2:3] op_sel:[1,0]
	v_pk_mul_f32 v[0:1], v[8:9], v[0:1] op_sel:[1,0]
	v_sub_f32_e32 v7, v113, v8
	v_pk_fma_f32 v[2:3], v[154:155], v[0:1], v[158:159]
	v_pk_fma_f32 v[0:1], v[152:153], v[4:5], v[156:157]
	v_sub_f32_e32 v5, v115, v8
	v_sub_f32_e32 v4, v114, v8
	v_sub_f32_e32 v6, v112, v8
	v_pk_mul_f32 v[12:13], v[8:9], v[6:7] op_sel:[1,0]
	v_pk_mul_f32 v[4:5], v[8:9], v[4:5] op_sel:[1,0]
	s_and_b64 vcc, exec, s[40:41]
	v_pk_fma_f32 v[6:7], v[146:147], v[4:5], v[150:151]
	v_pk_fma_f32 v[4:5], v[144:145], v[12:13], v[148:149]
	v_lshl_add_u64 v[10:11], v[10:11], 2, s[42:43]
	s_cbranch_vccnz .LBB0_532
	global_store_dwordx4 v[10:11], v[0:3], off nt
	global_store_dwordx4 v[10:11], v[4:7], off offset:16 nt
	s_cbranch_execnz .LBB0_243

;     __device__ __forceinline__ void fused(f32x4 (&acc)[2][2][4][2], const Unit& u, int wr, int wc, int fr, int fq, LAS unsigned char* lds, int wid, int lane) const {
;     ...
;             for (int m = 0; m < 4; ++m) { const int r = ai * HALF + wr * 64 + m * 16 + fr; const f32x2 sr = S[r]; const size_t off = (size_t)(u.pm * BM + r) * D + col0;
; #pragma unroll
;                 for (int bj = 0; bj < 2; ++bj) {
;                     const f32x4 y0 = (acc[ai][bj][m][0] - sr.x) * sr.y * gv[bj][0] + bv[bj][0], y1 = (acc[ai][bj][m][1] - sr.x) * sr.y * gv[bj][1] + bv[bj][1];
;                     if (xout) { *(f32x4*)(xout + off + bj * HALF) = y0; *(f32x4*)(xout + off + bj * HALF + 4) = y1; }
;                     else { u32x4 hw; hw.x = cvt_pk_h(y0[0], y0[1]); hw.y = cvt_pk_h(y0[2], y0[3]); hw.z = cvt_pk_h(y1[0], y1[1]); hw.w = cvt_pk_h(y1[2], y1[3]); *(u32x4*)(X16 + off + bj * HALF) = hw; } }
.LBB0_243:
	s_nop 0
	v_mov_b32_e32 v4, v9
	v_mov_b32_e32 v5, v9
	v_sub_f32_e32 v1, v103, v8
	v_sub_f32_e32 v0, v102, v8
	v_sub_f32_e32 v3, v101, v8
	v_sub_f32_e32 v2, v100, v8
	v_mov_b32_e32 v12, v9
	v_mov_b32_e32 v13, v9
	v_pk_mul_f32 v[6:7], v[4:5], v[2:3]
	v_pk_mul_f32 v[0:1], v[12:13], v[0:1]
	v_sub_f32_e32 v9, v97, v8
	v_pk_fma_f32 v[2:3], v[138:139], v[0:1], v[142:143]
	v_pk_fma_f32 v[0:1], v[136:137], v[6:7], v[140:141]
	v_sub_f32_e32 v7, v99, v8
	v_sub_f32_e32 v6, v98, v8
	v_sub_f32_e32 v8, v96, v8
	v_pk_mul_f32 v[4:5], v[4:5], v[8:9]
	v_pk_mul_f32 v[6:7], v[12:13], v[6:7]
	s_and_b64 vcc, exec, s[40:41]
	v_pk_fma_f32 v[6:7], v[50:51], v[6:7], v[54:55]
	v_pk_fma_f32 v[4:5], v[48:49], v[4:5], v[52:53]
	s_cbranch_vccnz .LBB0_533
	global_store_dwordx4 v[10:11], v[0:3], off offset:512 nt
	global_store_dwordx4 v[10:11], v[4:7], off offset:528 nt
	s_cbranch_execnz .LBB0_246

;     __device__ __forceinline__ void fused(f32x4 (&acc)[2][2][4][2], const Unit& u, int wr, int wc, int fr, int fq, LAS unsigned char* lds, int wid, int lane) const {
;     ...
;             for (int m = 0; m < 4; ++m) { const int r = ai * HALF + wr * 64 + m * 16 + fr; const f32x2 sr = S[r]; const size_t off = (size_t)(u.pm * BM + r) * D + col0;
; #pragma unroll
;                 for (int bj = 0; bj < 2; ++bj) {
;                     const f32x4 y0 = (acc[ai][bj][m][0] - sr.x) * sr.y * gv[bj][0] + bv[bj][0], y1 = (acc[ai][bj][m][1] - sr.x) * sr.y * gv[bj][1] + bv[bj][1];
;                     if (xout) { *(f32x4*)(xout + off + bj * HALF) = y0; *(f32x4*)(xout + off + bj * HALF + 4) = y1; }
;                     else { u32x4 hw; hw.x = cvt_pk_h(y0[0], y0[1]); hw.y = cvt_pk_h(y0[2], y0[3]); hw.z = cvt_pk_h(y1[0], y1[1]); hw.w = cvt_pk_h(y1[2], y1[3]); *(u32x4*)(X16 + off + bj * HALF) = hw; } }
.LBB0_246:
	ds_read_b64 v[8:9], v160 offset:9472
	s_nop 0
	v_add_u32_e32 v0, 0xa0, v190
	v_ashrrev_i32_e32 v1, 31, v0
	v_lshlrev_b64 v[0:1], 10, v[0:1]
	v_lshl_add_u64 v[10:11], v[0:1], 0, v[172:173]
	s_waitcnt lgkmcnt(0)
	v_sub_f32_e32 v1, v135, v8
	v_sub_f32_e32 v0, v134, v8
	v_sub_f32_e32 v3, v133, v8
	v_sub_f32_e32 v2, v132, v8
	v_pk_mul_f32 v[4:5], v[8:9], v[2:3] op_sel:[1,0]
	v_pk_mul_f32 v[0:1], v[8:9], v[0:1] op_sel:[1,0]
	v_sub_f32_e32 v7, v129, v8
	v_pk_fma_f32 v[2:3], v[154:155], v[0:1], v[158:159]
	v_pk_fma_f32 v[0:1], v[152:153], v[4:5], v[156:157]
	v_sub_f32_e32 v5, v131, v8
	v_sub_f32_e32 v4, v130, v8
	v_sub_f32_e32 v6, v128, v8
	v_pk_mul_f32 v[12:13], v[8:9], v[6:7] op_sel:[1,0]
	v_pk_mul_f32 v[4:5], v[8:9], v[4:5] op_sel:[1,0]
	s_and_b64 vcc, exec, s[40:41]
	v_pk_fma_f32 v[6:7], v[146:147], v[4:5], v[150:151]
	v_pk_fma_f32 v[4:5], v[144:145], v[12:13], v[148:149]
	v_lshl_add_u64 v[10:11], v[10:11], 2, s[42:43]
	s_cbranch_vccnz .LBB0_534
	global_store_dwordx4 v[10:11], v[0:3], off nt
	global_store_dwordx4 v[10:11], v[4:7], off offset:16 nt
	s_cbranch_execnz .LBB0_249

;     __device__ __forceinline__ void fused(f32x4 (&acc)[2][2][4][2], const Unit& u, int wr, int wc, int fr, int fq, LAS unsigned char* lds, int wid, int lane) const {
;     ...
;             for (int m = 0; m < 4; ++m) { const int r = ai * HALF + wr * 64 + m * 16 + fr; const f32x2 sr = S[r]; const size_t off = (size_t)(u.pm * BM + r) * D + col0;
; #pragma unroll
;                 for (int bj = 0; bj < 2; ++bj) {
;                     const f32x4 y0 = (acc[ai][bj][m][0] - sr.x) * sr.y * gv[bj][0] + bv[bj][0], y1 = (acc[ai][bj][m][1] - sr.x) * sr.y * gv[bj][1] + bv[bj][1];
;                     if (xout) { *(f32x4*)(xout + off + bj * HALF) = y0; *(f32x4*)(xout + off + bj * HALF + 4) = y1; }
;                     else { u32x4 hw; hw.x = cvt_pk_h(y0[0], y0[1]); hw.y = cvt_pk_h(y0[2], y0[3]); hw.z = cvt_pk_h(y1[0], y1[1]); hw.w = cvt_pk_h(y1[2], y1[3]); *(u32x4*)(X16 + off + bj * HALF) = hw; } }
.LBB0_249:
	s_nop 0
	v_mov_b32_e32 v4, v9
	v_mov_b32_e32 v5, v9
	v_sub_f32_e32 v1, v63, v8
	v_sub_f32_e32 v0, v62, v8
	v_sub_f32_e32 v3, v61, v8
	v_sub_f32_e32 v2, v60, v8
	v_mov_b32_e32 v12, v9
	v_mov_b32_e32 v13, v9
	v_pk_mul_f32 v[6:7], v[4:5], v[2:3]
	v_pk_mul_f32 v[0:1], v[12:13], v[0:1]
	v_sub_f32_e32 v9, v57, v8
	v_pk_fma_f32 v[2:3], v[138:139], v[0:1], v[142:143]
	v_pk_fma_f32 v[0:1], v[136:137], v[6:7], v[140:141]
	v_sub_f32_e32 v7, v59, v8
	v_sub_f32_e32 v6, v58, v8
	v_sub_f32_e32 v8, v56, v8
	v_pk_mul_f32 v[4:5], v[4:5], v[8:9]
	v_pk_mul_f32 v[6:7], v[12:13], v[6:7]
	s_and_b64 vcc, exec, s[40:41]
	v_pk_fma_f32 v[6:7], v[50:51], v[6:7], v[54:55]
	v_pk_fma_f32 v[4:5], v[48:49], v[4:5], v[52:53]
	s_cbranch_vccnz .LBB0_535
	global_store_dwordx4 v[10:11], v[0:3], off offset:512 nt
	global_store_dwordx4 v[10:11], v[4:7], off offset:528 nt
	s_cbranch_execnz .LBB0_252

;     __device__ __forceinline__ void fused(f32x4 (&acc)[2][2][4][2], const Unit& u, int wr, int wc, int fr, int fq, LAS unsigned char* lds, int wid, int lane) const {
;     ...
;             for (int m = 0; m < 4; ++m) { const int r = ai * HALF + wr * 64 + m * 16 + fr; const f32x2 sr = S[r]; const size_t off = (size_t)(u.pm * BM + r) * D + col0;
; #pragma unroll
;                 for (int bj = 0; bj < 2; ++bj) {
;                     const f32x4 y0 = (acc[ai][bj][m][0] - sr.x) * sr.y * gv[bj][0] + bv[bj][0], y1 = (acc[ai][bj][m][1] - sr.x) * sr.y * gv[bj][1] + bv[bj][1];
;                     if (xout) { *(f32x4*)(xout + off + bj * HALF) = y0; *(f32x4*)(xout + off + bj * HALF + 4) = y1; }
;                     else { u32x4 hw; hw.x = cvt_pk_h(y0[0], y0[1]); hw.y = cvt_pk_h(y0[2], y0[3]); hw.z = cvt_pk_h(y1[0], y1[1]); hw.w = cvt_pk_h(y1[2], y1[3]); *(u32x4*)(X16 + off + bj * HALF) = hw; } }
.LBB0_252:
	ds_read_b64 v[8:9], v160 offset:9600
	s_nop 0
	v_add_u32_e32 v0, 0xb0, v190
	v_ashrrev_i32_e32 v1, 31, v0
	v_lshlrev_b64 v[0:1], 10, v[0:1]
	v_lshl_add_u64 v[10:11], v[0:1], 0, v[172:173]
	s_waitcnt lgkmcnt(0)
	v_sub_f32_e32 v1, v47, v8
	v_sub_f32_e32 v0, v46, v8
	v_sub_f32_e32 v3, v45, v8
	v_sub_f32_e32 v2, v44, v8
	v_pk_mul_f32 v[4:5], v[8:9], v[2:3] op_sel:[1,0]
	v_pk_mul_f32 v[0:1], v[8:9], v[0:1] op_sel:[1,0]
	v_sub_f32_e32 v7, v41, v8
	v_pk_fma_f32 v[2:3], v[154:155], v[0:1], v[158:159]
	v_pk_fma_f32 v[0:1], v[152:153], v[4:5], v[156:157]
	v_sub_f32_e32 v5, v43, v8
	v_sub_f32_e32 v4, v42, v8
	v_sub_f32_e32 v6, v40, v8
	v_pk_mul_f32 v[12:13], v[8:9], v[6:7] op_sel:[1,0]
	v_pk_mul_f32 v[4:5], v[8:9], v[4:5] op_sel:[1,0]
	s_and_b64 vcc, exec, s[40:41]
	v_pk_fma_f32 v[6:7], v[146:147], v[4:5], v[150:151]
	v_pk_fma_f32 v[4:5], v[144:145], v[12:13], v[148:149]
	v_lshl_add_u64 v[10:11], v[10:11], 2, s[42:43]
	s_cbranch_vccnz .LBB0_536
	global_store_dwordx4 v[10:11], v[0:3], off nt
	global_store_dwordx4 v[10:11], v[4:7], off offset:16 nt
	s_cbranch_execnz .LBB0_255

;     __device__ __forceinline__ void fused(f32x4 (&acc)[2][2][4][2], const Unit& u, int wr, int wc, int fr, int fq, LAS unsigned char* lds, int wid, int lane) const {
;     ...
;             for (int m = 0; m < 4; ++m) { const int r = ai * HALF + wr * 64 + m * 16 + fr; const f32x2 sr = S[r]; const size_t off = (size_t)(u.pm * BM + r) * D + col0;
; #pragma unroll
;                 for (int bj = 0; bj < 2; ++bj) {
;                     const f32x4 y0 = (acc[ai][bj][m][0] - sr.x) * sr.y * gv[bj][0] + bv[bj][0], y1 = (acc[ai][bj][m][1] - sr.x) * sr.y * gv[bj][1] + bv[bj][1];
;                     if (xout) { *(f32x4*)(xout + off + bj * HALF) = y0; *(f32x4*)(xout + off + bj * HALF + 4) = y1; }
;                     else { u32x4 hw; hw.x = cvt_pk_h(y0[0], y0[1]); hw.y = cvt_pk_h(y0[2], y0[3]); hw.z = cvt_pk_h(y1[0], y1[1]); hw.w = cvt_pk_h(y1[2], y1[3]); *(u32x4*)(X16 + off + bj * HALF) = hw; } }
.LBB0_255:
	s_nop 0
	v_mov_b32_e32 v4, v9
	v_mov_b32_e32 v5, v9
	v_sub_f32_e32 v1, v39, v8
	v_sub_f32_e32 v0, v38, v8
	v_sub_f32_e32 v3, v37, v8
	v_sub_f32_e32 v2, v36, v8
	v_mov_b32_e32 v12, v9
	v_mov_b32_e32 v13, v9
	v_pk_mul_f32 v[6:7], v[4:5], v[2:3]
	v_pk_mul_f32 v[0:1], v[12:13], v[0:1]
	v_sub_f32_e32 v9, v33, v8
	v_pk_fma_f32 v[2:3], v[138:139], v[0:1], v[142:143]
	v_pk_fma_f32 v[0:1], v[136:137], v[6:7], v[140:141]
	v_sub_f32_e32 v7, v35, v8
	v_sub_f32_e32 v6, v34, v8
	v_sub_f32_e32 v8, v32, v8
	v_pk_mul_f32 v[4:5], v[4:5], v[8:9]
	v_pk_mul_f32 v[6:7], v[12:13], v[6:7]
	s_and_b64 vcc, exec, s[40:41]
	v_pk_fma_f32 v[6:7], v[50:51], v[6:7], v[54:55]
	v_pk_fma_f32 v[4:5], v[48:49], v[4:5], v[52:53]
	s_cbranch_vccnz .LBB0_537
	global_store_dwordx4 v[10:11], v[0:3], off offset:512 nt
	global_store_dwordx4 v[10:11], v[4:7], off offset:528 nt
	s_cbranch_execnz .LBB0_258

; __global__ void __launch_bounds__(512, 2) mega_fwd(Args args) {
;     ...
;             for (int m0 = gw; m0 < TC; m0 += 4 * NGW) {
;                 f32x4 v[4][4];
; #pragma unroll
;                 for (int r = 0; r < 4; ++r) { const int mm = m0 + r * NGW; const size_t m = (size_t)(mm < TC ? mm : m0);
; #pragma unroll
;                     for (int j = 0; j < 4; ++j) v[r][j] = *((const f32x4*)(xin + m * D) + lane + 64 * j); }
; #pragma unroll
;                 for (int r = 0; r < 4; ++r) { const int mm = m0 + r * NGW; if (mm >= TC) continue;
; #pragma unroll
;                     for (int j = 0; j < 4; ++j) { u32x2 w; w.x = cvt_pk_h(v[r][j][0], v[r][j][1]); w.y = cvt_pk_h(v[r][j][2], v[r][j][3]); *((u32x2*)(xnext + (size_t)mm * D) + lane + 64 * j) = w; } }
;             }
.LBB0_465:
	s_add_i32 s38, s84, s0
	s_cmpk_lt_i32 s38, 0x4000
	s_cselect_b32 s4, s38, s0
	s_ashr_i32 s5, s4, 31
	s_lshl_b64 s[4:5], s[4:5], 12
	s_add_i32 s12, s33, s0
	s_cmpk_lt_i32 s12, 0x4000
	v_lshl_add_u64 v[0:1], v[48:49], 0, s[4:5]
	s_cselect_b32 s4, s12, s0
	s_ashr_i32 s5, s4, 31
	s_lshl_b64 s[4:5], s[4:5], 12
	s_add_i32 s8, s21, s0
	s_cmpk_lt_i32 s8, 0x4000
	global_load_dwordx4 v[44:47], v[0:1], off nt
	global_load_dwordx4 v[40:43], v[0:1], off offset:1024 nt
	global_load_dwordx4 v[36:39], v[0:1], off offset:2048 nt
	global_load_dwordx4 v[32:35], v[0:1], off offset:3072 nt
	v_lshl_add_u64 v[0:1], v[48:49], 0, s[4:5]
	s_cselect_b32 s4, s8, s0
	s_ashr_i32 s5, s4, 31
	s_lshl_b64 s[4:5], s[4:5], 12
	s_ashr_i32 s1, s0, 31
	global_load_dwordx4 v[28:31], v[0:1], off nt
	global_load_dwordx4 v[24:27], v[0:1], off offset:1024 nt
	global_load_dwordx4 v[16:19], v[0:1], off offset:2048 nt
	global_load_dwordx4 v[8:11], v[0:1], off offset:3072 nt
	v_lshl_add_u64 v[0:1], v[48:49], 0, s[4:5]
	s_lshl_b64 s[4:5], s[0:1], 12
	global_load_dwordx4 v[20:23], v[0:1], off nt
	global_load_dwordx4 v[12:15], v[0:1], off offset:1024 nt
	global_load_dwordx4 v[4:7], v[0:1], off offset:2048 nt
	s_nop 0
	global_load_dwordx4 v[0:3], v[0:1], off offset:3072 nt
	v_lshl_add_u64 v[64:65], v[48:49], 0, s[4:5]
	global_load_dwordx4 v[52:55], v[64:65], off offset:3072 nt
	global_load_dwordx4 v[56:59], v[64:65], off offset:2048 nt
	global_load_dwordx4 v[60:63], v[64:65], off offset:1024 nt
	s_nop 0
	global_load_dwordx4 v[64:67], v[64:65], off nt
	s_lshl_b64 s[4:5], s[0:1], 11
	v_lshl_add_u64 v[68:69], v[50:51], 0, s[4:5]
	s_cmpk_gt_i32 s38, 0x3fff
	s_waitcnt vmcnt(0)
	v_cvt_pk_f16_f32 v52, v52, v53
	v_cvt_pk_f16_f32 v56, v56, v57
	v_cvt_pk_f16_f32 v60, v60, v61
	v_cvt_pk_f16_f32 v64, v64, v65
	v_cvt_pk_f16_f32 v65, v66, v67
	v_cvt_pk_f16_f32 v61, v62, v63
	v_cvt_pk_f16_f32 v57, v58, v59
	v_cvt_pk_f16_f32 v53, v54, v55
	global_store_dwordx2 v[68:69], v[64:65], off
	global_store_dwordx2 v[68:69], v[60:61], off offset:512
	global_store_dwordx2 v[68:69], v[56:57], off offset:1024
	global_store_dwordx2 v[68:69], v[52:53], off offset:1536
	s_cbranch_scc0 .LBB0_468
	s_cmpk_gt_i32 s12, 0x3fff
	s_cbranch_scc0 .LBB0_469
